# norm phases, context rows: the 16 partial-sum loads + 4 gate loads issued together (one wait) instead of 12 serialized load-pair/vmcnt(0) steps; same f32 add order
# speedup vs baseline: 1.0107x; 1.0049x over previous
; __device__ __forceinline__ void norm_phase(const float* xlat, const float* xctx, const float* gvec, const float* mod, int sh_off, int sc_off, bf16_t* H, int nrows,
;                                            const float* part, const float* pgate, float* xctx_out, int row_lo) {
;     ...
;         if (part != nullptr && row >= NLAT) {
; #pragma unroll
;             for (int j = 0; j < 4; ++j) {
;                 const size_t o = (size_t)(row - NLAT) * DM + 4 * lane + 256 * j;
;                 const f32x4 ps = (*(const f32x4*)(part + o) + *(const f32x4*)(part + (size_t)NCTX * DM + o)) + (*(const f32x4*)(part + (size_t)2 * NCTX * DM + o) + *(const f32x4*)(part + (size_t)3 * NCTX * DM + o));
;                 v[j] = v[j] + *(const f32x4*)(pgate + 4 * lane + 256 * j) * ps;
;                 *(f32x4*)(xctx_out + o) = v[j];
;             }
.Ln1_join:
	s_or_b64 exec, exec, s[12:13]
	s_movk_i32 s0, 0x3fff
	v_cmp_lt_i32_e64 s[0:1], s0, v97
	s_and_b64 s[12:13], s[4:5], s[0:1]
	s_and_saveexec_b64 s[0:1], s[12:13]
	s_cbranch_execz .LBB0_175
	v_mov_b32_e32 v97, v161
	v_lshlrev_b64 v[96:97], 12, v[96:97]
	v_readlane_b32 s12, v253, 18
	v_readlane_b32 s13, v253, 19
	v_lshl_or_b32 v96, v80, 2, v96
	v_mov_b32_e32 v251, v97
	v_lshl_add_u64 v[248:249], s[14:15], 0, v[96:97]
	global_load_dwordx4 v[122:125], v[248:249], off
	v_lshl_add_u64 v[248:249], s[12:13], 0, v[96:97]
	global_load_dwordx4 v[126:129], v[248:249], off
	v_lshl_add_u64 v[248:249], s[46:47], 0, v[96:97]
	global_load_dwordx4 v[130:133], v[248:249], off
	v_lshl_add_u64 v[248:249], s[66:67], 0, v[96:97]
	global_load_dwordx4 v[134:137], v[248:249], off
	global_load_dwordx4 v[138:141], v[82:83], off
	v_or_b32_e32 v250, 0x400, v96
	v_lshl_add_u64 v[248:249], s[14:15], 0, v[250:251]
	global_load_dwordx4 v[142:145], v[248:249], off
	v_lshl_add_u64 v[248:249], s[12:13], 0, v[250:251]
	global_load_dwordx4 v[146:149], v[248:249], off
	v_lshl_add_u64 v[248:249], s[46:47], 0, v[250:251]
	global_load_dwordx4 v[150:153], v[248:249], off
	v_lshl_add_u64 v[248:249], s[66:67], 0, v[250:251]
	global_load_dwordx4 v[162:165], v[248:249], off
	global_load_dwordx4 v[166:169], v[82:83], off offset:1024
	v_or_b32_e32 v250, 0x800, v96
	v_lshl_add_u64 v[248:249], s[14:15], 0, v[250:251]
	global_load_dwordx4 v[170:173], v[248:249], off
	v_lshl_add_u64 v[248:249], s[12:13], 0, v[250:251]
	global_load_dwordx4 v[174:177], v[248:249], off
	v_lshl_add_u64 v[248:249], s[46:47], 0, v[250:251]
	global_load_dwordx4 v[178:181], v[248:249], off
	v_lshl_add_u64 v[248:249], s[66:67], 0, v[250:251]
	global_load_dwordx4 v[182:185], v[248:249], off
	global_load_dwordx4 v[186:189], v[82:83], off offset:2048
	v_or_b32_e32 v250, 0xc00, v96
	v_lshl_add_u64 v[248:249], s[14:15], 0, v[250:251]
	global_load_dwordx4 v[216:219], v[248:249], off
	v_lshl_add_u64 v[248:249], s[12:13], 0, v[250:251]
	global_load_dwordx4 v[220:223], v[248:249], off
	v_lshl_add_u64 v[248:249], s[46:47], 0, v[250:251]
	global_load_dwordx4 v[224:227], v[248:249], off
	v_lshl_add_u64 v[248:249], s[66:67], 0, v[250:251]
	global_load_dwordx4 v[228:231], v[248:249], off
	global_load_dwordx4 v[232:235], v[82:83], off offset:3072
	s_waitcnt vmcnt(0)
	v_pk_add_f32 v[236:237], v[122:123], v[126:127]
	v_pk_add_f32 v[238:239], v[124:125], v[128:129]
	v_pk_add_f32 v[240:241], v[130:131], v[134:135]
	v_pk_add_f32 v[242:243], v[132:133], v[136:137]
	v_pk_add_f32 v[236:237], v[236:237], v[240:241]
	v_pk_add_f32 v[238:239], v[238:239], v[242:243]
	v_pk_fma_f32 v[14:15], v[140:141], v[238:239], v[14:15]
	v_pk_fma_f32 v[12:13], v[138:139], v[236:237], v[12:13]
	v_lshl_add_u64 v[248:249], s[26:27], 0, v[96:97]
	global_store_dwordx4 v[248:249], v[12:15], off
	v_pk_add_f32 v[236:237], v[142:143], v[146:147]
	v_pk_add_f32 v[238:239], v[144:145], v[148:149]
	v_pk_add_f32 v[240:241], v[150:151], v[162:163]
	v_pk_add_f32 v[242:243], v[152:153], v[164:165]
	v_pk_add_f32 v[236:237], v[236:237], v[240:241]
	v_pk_add_f32 v[238:239], v[238:239], v[242:243]
	v_pk_fma_f32 v[10:11], v[168:169], v[238:239], v[10:11]
	v_pk_fma_f32 v[8:9], v[166:167], v[236:237], v[8:9]
	v_or_b32_e32 v250, 0x400, v96
	v_lshl_add_u64 v[248:249], s[26:27], 0, v[250:251]
	global_store_dwordx4 v[248:249], v[8:11], off
	v_pk_add_f32 v[236:237], v[170:171], v[174:175]
	v_pk_add_f32 v[238:239], v[172:173], v[176:177]
	v_pk_add_f32 v[240:241], v[178:179], v[182:183]
	v_pk_add_f32 v[242:243], v[180:181], v[184:185]
	v_pk_add_f32 v[236:237], v[236:237], v[240:241]
	v_pk_add_f32 v[238:239], v[238:239], v[242:243]
	v_pk_fma_f32 v[6:7], v[188:189], v[238:239], v[6:7]
	v_pk_fma_f32 v[4:5], v[186:187], v[236:237], v[4:5]
	v_or_b32_e32 v250, 0x800, v96
	v_lshl_add_u64 v[248:249], s[26:27], 0, v[250:251]
	global_store_dwordx4 v[248:249], v[4:7], off
	v_pk_add_f32 v[236:237], v[216:217], v[220:221]
	v_pk_add_f32 v[238:239], v[218:219], v[222:223]
	v_pk_add_f32 v[240:241], v[224:225], v[228:229]
	v_pk_add_f32 v[242:243], v[226:227], v[230:231]
	v_pk_add_f32 v[236:237], v[236:237], v[240:241]
	v_pk_add_f32 v[238:239], v[238:239], v[242:243]
	v_pk_fma_f32 v[2:3], v[234:235], v[238:239], v[2:3]
	v_pk_fma_f32 v[0:1], v[232:233], v[236:237], v[0:1]
	v_or_b32_e32 v250, 0xc00, v96
	v_lshl_add_u64 v[248:249], s[26:27], 0, v[250:251]
	global_store_dwordx4 v[248:249], v[0:3], off
	s_branch .LBB0_175

; __device__ __forceinline__ void norm_phase(const float* xlat, const float* xctx, const float* gvec, const float* mod, int sh_off, int sc_off, bf16_t* H, int nrows,
;                                            const float* part, const float* pgate, float* xctx_out, int row_lo) {
;     ...
;         const float* mp = mod + bb * 6144;
;         f32x4 gg[4], sc[4], sh[4];
; #pragma unroll
;         for (int j = 0; j < 4; ++j) { const int col = 4 * lane + 256 * j; gg[j] = *(const f32x4*)(gvec + col); sc[j] = *(const f32x4*)(mp + sc_off + col); sh[j] = *(const f32x4*)(mp + sh_off + col); }
;         if (part != nullptr && row >= NLAT) {
; #pragma unroll
;             for (int j = 0; j < 4; ++j) {
;                 const size_t o = (size_t)(row - NLAT) * DM + 4 * lane + 256 * j;
;                 const f32x4 ps = (*(const f32x4*)(part + o) + *(const f32x4*)(part + (size_t)NCTX * DM + o)) + (*(const f32x4*)(part + (size_t)2 * NCTX * DM + o) + *(const f32x4*)(part + (size_t)3 * NCTX * DM + o));
;                 v[j] = v[j] + *(const f32x4*)(pgate + 4 * lane + 256 * j) * ps;
;                 *(f32x4*)(xctx_out + o) = v[j];
;             }
.LBB0_1140:
	s_or_b64 exec, exec, s[12:13]
	v_add_u32_e32 v97, 0x4000, v96
	v_min_i32_e32 v32, 0x4000, v97
	v_ashrrev_i32_e32 v32, 11, v32
	v_mul_i32_i24_e32 v32, 0x1800, v32
	v_ashrrev_i32_e32 v33, 31, v32
	v_lshl_add_u64 v[32:33], v[32:33], 2, s[48:49]
	s_mov_b64 s[0:1], 0x4000
	v_lshl_add_u64 v[34:35], v[32:33], 0, s[0:1]
	s_mov_b64 s[0:1], 0x3000
	v_lshl_add_u64 v[32:33], v[32:33], 0, s[0:1]
	v_lshl_add_u64 v[36:37], v[34:35], 0, v[160:161]
	v_lshl_add_u64 v[38:39], v[32:33], 0, v[160:161]
	v_mov_b32_e32 v85, v161
	global_load_dwordx4 v[76:79], v[36:37], off
	global_load_dwordx4 v[68:71], v[38:39], off
	global_load_dwordx4 v[72:75], v[92:93], off
	global_load_dwordx4 v[60:63], v[92:93], off offset:1024
	v_lshl_add_u64 v[36:37], v[34:35], 0, v[84:85]
	v_lshl_add_u64 v[38:39], v[32:33], 0, v[84:85]
	v_mov_b32_e32 v87, v161
	global_load_dwordx4 v[64:67], v[36:37], off
	global_load_dwordx4 v[56:59], v[38:39], off
	v_lshl_add_u64 v[36:37], v[34:35], 0, v[86:87]
	v_lshl_add_u64 v[38:39], v[32:33], 0, v[86:87]
	global_load_dwordx4 v[48:51], v[36:37], off
	global_load_dwordx4 v[44:47], v[38:39], off
	global_load_dwordx4 v[52:55], v[92:93], off offset:2048
	s_nop 0
	global_load_dwordx4 v[36:39], v[92:93], off offset:3072
	v_mov_b32_e32 v89, v161
	v_lshl_add_u64 v[34:35], v[34:35], 0, v[88:89]
	v_lshl_add_u64 v[32:33], v[32:33], 0, v[88:89]
	global_load_dwordx4 v[40:43], v[34:35], off
	s_nop 0
	global_load_dwordx4 v[32:35], v[32:33], off
	s_movk_i32 s0, 0x3fff
	v_readlane_b32 s12, v255, 26
	v_cmp_lt_i32_e64 s[0:1], s0, v97
	v_readlane_b32 s13, v255, 27
	s_and_b64 s[12:13], s[12:13], s[0:1]
	s_and_saveexec_b64 s[0:1], s[12:13]
	s_cbranch_execz .LBB0_1137
	v_mov_b32_e32 v97, v161
	v_lshlrev_b64 v[96:97], 12, v[96:97]
	v_lshl_or_b32 v96, v80, 2, v96
	v_mov_b32_e32 v251, v97
	v_lshl_add_u64 v[248:249], s[22:23], 0, v[96:97]
	global_load_dwordx4 v[122:125], v[248:249], off
	v_lshl_add_u64 v[248:249], s[10:11], 0, v[96:97]
	global_load_dwordx4 v[126:129], v[248:249], off
	v_lshl_add_u64 v[248:249], s[46:47], 0, v[96:97]
	global_load_dwordx4 v[130:133], v[248:249], off
	v_lshl_add_u64 v[248:249], s[50:51], 0, v[96:97]
	global_load_dwordx4 v[134:137], v[248:249], off
	global_load_dwordx4 v[138:141], v[90:91], off
	v_or_b32_e32 v250, 0x400, v96
	v_lshl_add_u64 v[248:249], s[22:23], 0, v[250:251]
	global_load_dwordx4 v[142:145], v[248:249], off
	v_lshl_add_u64 v[248:249], s[10:11], 0, v[250:251]
	global_load_dwordx4 v[146:149], v[248:249], off
	v_lshl_add_u64 v[248:249], s[46:47], 0, v[250:251]
	global_load_dwordx4 v[150:153], v[248:249], off
	v_lshl_add_u64 v[248:249], s[50:51], 0, v[250:251]
	global_load_dwordx4 v[162:165], v[248:249], off
	global_load_dwordx4 v[166:169], v[90:91], off offset:1024
	v_or_b32_e32 v250, 0x800, v96
	v_lshl_add_u64 v[248:249], s[22:23], 0, v[250:251]
	global_load_dwordx4 v[170:173], v[248:249], off
	v_lshl_add_u64 v[248:249], s[10:11], 0, v[250:251]
	global_load_dwordx4 v[174:177], v[248:249], off
	v_lshl_add_u64 v[248:249], s[46:47], 0, v[250:251]
	global_load_dwordx4 v[178:181], v[248:249], off
	v_lshl_add_u64 v[248:249], s[50:51], 0, v[250:251]
	global_load_dwordx4 v[182:185], v[248:249], off
	global_load_dwordx4 v[186:189], v[90:91], off offset:2048
	v_or_b32_e32 v250, 0xc00, v96
	v_lshl_add_u64 v[248:249], s[22:23], 0, v[250:251]
	global_load_dwordx4 v[216:219], v[248:249], off
	v_lshl_add_u64 v[248:249], s[10:11], 0, v[250:251]
	global_load_dwordx4 v[220:223], v[248:249], off
	v_lshl_add_u64 v[248:249], s[46:47], 0, v[250:251]
	global_load_dwordx4 v[224:227], v[248:249], off
	v_lshl_add_u64 v[248:249], s[50:51], 0, v[250:251]
	global_load_dwordx4 v[228:231], v[248:249], off
	global_load_dwordx4 v[232:235], v[90:91], off offset:3072
	s_waitcnt vmcnt(0)
	v_pk_add_f32 v[236:237], v[122:123], v[126:127]
	v_pk_add_f32 v[238:239], v[124:125], v[128:129]
	v_pk_add_f32 v[240:241], v[130:131], v[134:135]
	v_pk_add_f32 v[242:243], v[132:133], v[136:137]
	v_pk_add_f32 v[236:237], v[236:237], v[240:241]
	v_pk_add_f32 v[238:239], v[238:239], v[242:243]
	v_pk_fma_f32 v[14:15], v[140:141], v[238:239], v[14:15]
	v_pk_fma_f32 v[12:13], v[138:139], v[236:237], v[12:13]
	v_lshl_add_u64 v[248:249], s[26:27], 0, v[96:97]
	global_store_dwordx4 v[248:249], v[12:15], off
	v_pk_add_f32 v[236:237], v[142:143], v[146:147]
	v_pk_add_f32 v[238:239], v[144:145], v[148:149]
	v_pk_add_f32 v[240:241], v[150:151], v[162:163]
	v_pk_add_f32 v[242:243], v[152:153], v[164:165]
	v_pk_add_f32 v[236:237], v[236:237], v[240:241]
	v_pk_add_f32 v[238:239], v[238:239], v[242:243]
	v_pk_fma_f32 v[10:11], v[168:169], v[238:239], v[10:11]
	v_pk_fma_f32 v[8:9], v[166:167], v[236:237], v[8:9]
	v_or_b32_e32 v250, 0x400, v96
	v_lshl_add_u64 v[248:249], s[26:27], 0, v[250:251]
	global_store_dwordx4 v[248:249], v[8:11], off
	v_pk_add_f32 v[236:237], v[170:171], v[174:175]
	v_pk_add_f32 v[238:239], v[172:173], v[176:177]
	v_pk_add_f32 v[240:241], v[178:179], v[182:183]
	v_pk_add_f32 v[242:243], v[180:181], v[184:185]
	v_pk_add_f32 v[236:237], v[236:237], v[240:241]
	v_pk_add_f32 v[238:239], v[238:239], v[242:243]
	v_pk_fma_f32 v[6:7], v[188:189], v[238:239], v[6:7]
	v_pk_fma_f32 v[4:5], v[186:187], v[236:237], v[4:5]
	v_or_b32_e32 v250, 0x800, v96
	v_lshl_add_u64 v[248:249], s[26:27], 0, v[250:251]
	global_store_dwordx4 v[248:249], v[4:7], off
	v_pk_add_f32 v[236:237], v[216:217], v[220:221]
	v_pk_add_f32 v[238:239], v[218:219], v[222:223]
	v_pk_add_f32 v[240:241], v[224:225], v[228:229]
	v_pk_add_f32 v[242:243], v[226:227], v[230:231]
	v_pk_add_f32 v[236:237], v[236:237], v[240:241]
	v_pk_add_f32 v[238:239], v[238:239], v[242:243]
	v_pk_fma_f32 v[2:3], v[234:235], v[238:239], v[2:3]
	v_pk_fma_f32 v[0:1], v[232:233], v[236:237], v[0:1]
	v_or_b32_e32 v250, 0xc00, v96
	v_lshl_add_u64 v[248:249], s[26:27], 0, v[250:251]
	global_store_dwordx4 v[248:249], v[0:3], off
	s_branch .LBB0_1137
